# attention static-priority version plus counted lgkmcnt waits in the QK chains (levers 4 and 1 combined)
# baseline (speedup 1.0000x reference)
; #define LAS __attribute__((address_space(3)))
; #define WG_BAR() do { asm volatile("s_waitcnt lgkmcnt(0)" ::: "memory"); __builtin_amdgcn_s_barrier(); asm volatile("" ::: "memory"); } while (0)
; template <int MODE, class Dec>
; __device__ __forceinline__ void attn_phase(const Frame& F, const bf16* Q, const bf16* K, const bf16* V, int nunits, const Dec dec, const bf16* O3, const float* L2, const float* L3) {
;     ...
;         WG_BAR();
;         const float sl = exp2f(-0.5f * (float)(h + 1)) * LOG2E * (float)d, cb = -sl * (float)(128 + ql - 4 * g);
;         f32x4 s[9];
;         __builtin_amdgcn_s_setprio(1);
; #pragma unroll
;         for (int tt = 0; tt < 9; ++tt) {
;             s[tt] = (f32x4){fmaf(sl, (float)(16 * tt), cb), fmaf(sl, (float)(16 * tt + 1), cb), fmaf(sl, (float)(16 * tt + 2), cb), fmaf(sl, (float)(16 * tt + 3), cb)};
; #pragma unroll
;             for (int ks = 0; ks < 4; ++ks) { const bf16x8 a = *(const LAS bf16x8*)(kb + ksw[ks] + tt * 4096); s[tt] = __builtin_amdgcn_mfma_f32_16x16x32_bf16(a, qf[ks], s[tt], 0, 0, 0); }
;         }
;         __builtin_amdgcn_s_setprio(0);
;         WG_BAR();
;         v2u a2[8], a3[8]; float l2v = 0.f, l3v = 0.f;
;         bf16* op = cur.Og + qrow * (size_t)cur.ldo + h * 128 + 4 * g;
;         if (MODE == 1) { const bf16* o3p = O3 + qrow * 2048 + h * 128 + 4 * g;
; #pragma unroll
;             for (int dt = 0; dt < 8; ++dt) { a2[dt] = *(const v2u*)(op + 16 * dt); a3[dt] = *(const v2u*)(o3p + 16 * dt); }
;             l2v = L2[qrow * 16 + h]; l3v = L3[qrow * 16 + h]; }
;         if (has_next) { attn_issue<false>(F, K, nxt, 0);
.LBB0_448:
	s_add_i32 s34, s56, 1
	v_cvt_f32_u32_e32 v16, s34
	s_mov_b32 s34, 0xc2fc0000
	s_waitcnt lgkmcnt(0)
	s_barrier
	v_mul_f32_e32 v17, -0.5, v16
	v_cmp_gt_f32_e32 vcc, s34, v17
	s_and_b64 s[34:35], vcc, exec
	s_cselect_b32 s34, 0xffffffc0, 0
	v_cndmask_b32_e32 v17, 0, v100, vcc
	v_fmac_f32_e32 v17, -0.5, v16
	v_exp_f32_e32 v16, v17
	v_cvt_f32_u32_e32 v17, s82
	v_ldexp_f32 v16, v16, s34
	v_mul_f32_e32 v16, 0x3fb8aa3b, v16
	v_mul_f32_e32 v80, v16, v17
	v_mul_f32_e64 v82, v81, -v80
	s_nop 0
	ds_read_b128 v[16:19], v96
	ds_read_b128 v[20:23], v96 offset:4096
	s_mov_b32 s34, 2.0
	s_mov_b32 s35, 0x40400000
	v_pk_fma_f32 v[26:27], v[80:81], s[34:35], v[82:83] op_sel_hi:[0,1,0]
	s_mov_b32 s34, 0x41900000
	v_fma_f32 v24, 0, v80, v82
	v_fma_f32 v25, v81, -v80, v80
	s_mov_b32 s35, 0x41980000
	ds_read_b128 v[48:51], v96 offset:32768
	ds_read_b128 v[28:31], v96 offset:8192
	s_waitcnt lgkmcnt(2)
	v_mfma_f32_16x16x32_bf16 v[16:19], v[16:19], v[12:15], v[24:27]
	s_nop 2
	v_fma_f32 v26, v80, s34, v82
	v_fma_f32 v27, v80, s35, v82
	s_mov_b32 s34, 0x41800000
	s_mov_b32 s35, 0x41880000
	v_pk_fma_f32 v[24:25], v[80:81], s[34:35], v[82:83] op_sel_hi:[0,1,0]
	s_mov_b32 s34, 0x42080000
	s_mov_b32 s35, 0x420c0000
	v_mfma_f32_16x16x32_bf16 v[20:23], v[20:23], v[12:15], v[24:27]
	s_nop 2
	ds_read_b128 v[24:27], v97
	ds_read_b128 v[32:35], v97 offset:4096
	s_waitcnt lgkmcnt(1)
	v_mfma_f32_16x16x32_bf16 v[16:19], v[24:27], v[8:11], v[16:19]
	ds_read_b128 v[24:27], v98
	ds_read_b128 v[104:107], v98 offset:32768
	s_waitcnt lgkmcnt(1)
	v_mfma_f32_16x16x32_bf16 v[16:19], v[24:27], v[4:7], v[16:19]
	ds_read_b128 v[24:27], v99
	ds_read_b128 v[36:39], v99 offset:4096
	s_waitcnt lgkmcnt(1)
	v_mfma_f32_16x16x32_bf16 v[44:47], v[24:27], v[0:3], v[16:19]
	v_mfma_f32_16x16x32_bf16 v[16:19], v[32:35], v[8:11], v[20:23]
	s_nop 2
	ds_read_b128 v[20:23], v98 offset:4096
	ds_read_b128 v[24:27], v98 offset:8192
	s_waitcnt lgkmcnt(1)
	v_mfma_f32_16x16x32_bf16 v[16:19], v[20:23], v[4:7], v[16:19]
	v_mfma_f32_16x16x32_bf16 v[36:39], v[36:39], v[0:3], v[16:19]
	s_nop 6
	v_fma_f32 v18, v80, s34, v82
	v_fma_f32 v19, v80, s35, v82
	s_mov_b32 s34, 0x42000000
	s_mov_b32 s35, 0x42040000
	v_pk_fma_f32 v[16:17], v[80:81], s[34:35], v[82:83] op_sel_hi:[0,1,0]
	s_mov_b32 s34, 0x42480000
	s_mov_b32 s35, 0x424c0000
	v_mfma_f32_16x16x32_bf16 v[16:19], v[28:31], v[12:15], v[16:19]
	ds_read_b128 v[20:23], v97 offset:8192
	ds_read_b128 v[28:31], v97 offset:12288
	s_waitcnt lgkmcnt(1)
	v_mfma_f32_16x16x32_bf16 v[16:19], v[20:23], v[8:11], v[16:19]
	ds_read_b128 v[20:23], v99 offset:8192
	v_mfma_f32_16x16x32_bf16 v[16:19], v[24:27], v[4:7], v[16:19]
	ds_read_b128 v[24:27], v96 offset:12288
	ds_read_b128 v[40:43], v99 offset:12288
	s_waitcnt lgkmcnt(1)
	v_mfma_f32_16x16x32_bf16 v[32:35], v[20:23], v[0:3], v[16:19]
	ds_read_b128 v[20:23], v96 offset:16384
	s_nop 2
	v_pk_fma_f32 v[18:19], v[80:81], s[34:35], v[82:83] op_sel_hi:[0,1,0]
	s_mov_b32 s34, 0x42400000
	s_mov_b32 s35, 0x42440000
	v_pk_fma_f32 v[16:17], v[80:81], s[34:35], v[82:83] op_sel_hi:[0,1,0]
	s_mov_b32 s34, 0x42840000
	s_mov_b32 s35, 0x42860000
	v_mfma_f32_16x16x32_bf16 v[16:19], v[24:27], v[12:15], v[16:19]
	ds_read_b128 v[24:27], v98 offset:12288
	ds_read_b128 v[108:111], v98 offset:16384
	v_mfma_f32_16x16x32_bf16 v[16:19], v[28:31], v[8:11], v[16:19]
	s_waitcnt lgkmcnt(1)
	v_mfma_f32_16x16x32_bf16 v[16:19], v[24:27], v[4:7], v[16:19]
	v_mfma_f32_16x16x32_bf16 v[28:31], v[40:43], v[0:3], v[16:19]
	s_nop 6
	v_fma_f32 v18, v80, s34, v82
	v_fma_f32 v19, v80, s35, v82
	s_mov_b32 s34, 0x42800000
	s_mov_b32 s35, 0x42820000
	v_pk_fma_f32 v[16:17], v[80:81], s[34:35], v[82:83] op_sel_hi:[0,1,0]
	s_mov_b32 s34, 0x42a40000
	s_mov_b32 s35, 0x42a60000
	v_mfma_f32_16x16x32_bf16 v[16:19], v[20:23], v[12:15], v[16:19]
	ds_read_b128 v[20:23], v97 offset:16384
	ds_read_b128 v[40:43], v97 offset:20480
	s_waitcnt lgkmcnt(1)
	v_mfma_f32_16x16x32_bf16 v[16:19], v[20:23], v[8:11], v[16:19]
	ds_read_b128 v[20:23], v99 offset:16384
	v_mfma_f32_16x16x32_bf16 v[16:19], v[108:111], v[4:7], v[16:19]
	ds_read_b128 v[108:111], v96 offset:20480
	ds_read_b128 v[112:115], v99 offset:20480
	ds_read_b128 v[116:119], v96 offset:24576
	s_waitcnt lgkmcnt(2)
	v_mfma_f32_16x16x32_bf16 v[24:27], v[20:23], v[0:3], v[16:19]
	s_nop 2
	v_fma_f32 v18, v80, s34, v82
	v_fma_f32 v19, v80, s35, v82
	s_mov_b32 s34, 0x42a00000
	s_mov_b32 s35, 0x42a20000
	v_pk_fma_f32 v[16:17], v[80:81], s[34:35], v[82:83] op_sel_hi:[0,1,0]
	s_mov_b32 s34, 0x42c40000
	s_mov_b32 s35, 0x42c60000
	v_mfma_f32_16x16x32_bf16 v[16:19], v[108:111], v[12:15], v[16:19]
	v_mfma_f32_16x16x32_bf16 v[16:19], v[40:43], v[8:11], v[16:19]
	ds_read_b128 v[20:23], v98 offset:20480
	ds_read_b128 v[40:43], v98 offset:24576
	s_waitcnt lgkmcnt(1)
	v_mfma_f32_16x16x32_bf16 v[16:19], v[20:23], v[4:7], v[16:19]
	v_mfma_f32_16x16x32_bf16 v[20:23], v[112:115], v[0:3], v[16:19]
	ds_read_b128 v[108:111], v97 offset:24576
	ds_read_b128 v[112:115], v97 offset:28672
	s_nop 4
	v_pk_fma_f32 v[18:19], v[80:81], s[34:35], v[82:83] op_sel_hi:[0,1,0]
	v_pk_fma_f32 v[16:17], v[80:81], s[54:55], v[82:83] op_sel_hi:[0,1,0]
	s_nop 1
	v_mfma_f32_16x16x32_bf16 v[16:19], v[116:119], v[12:15], v[16:19]
	s_waitcnt lgkmcnt(1)
	v_mfma_f32_16x16x32_bf16 v[16:19], v[108:111], v[8:11], v[16:19]
	ds_read_b128 v[108:111], v99 offset:24576
	v_mfma_f32_16x16x32_bf16 v[16:19], v[40:43], v[4:7], v[16:19]
	ds_read_b128 v[40:43], v96 offset:28672
	ds_read_b128 v[116:119], v99 offset:28672
	ds_read_b128 v[120:123], v97 offset:32768
	s_waitcnt lgkmcnt(2)
	v_mfma_f32_16x16x32_bf16 v[16:19], v[108:111], v[0:3], v[16:19]
	v_fma_f32 v110, v80, s38, v82
	v_fma_f32 v111, v80, s39, v82
	v_pk_fma_f32 v[108:109], v[80:81], s[40:41], v[82:83] op_sel_hi:[0,1,0]
	s_nop 1
	v_mfma_f32_16x16x32_bf16 v[40:43], v[40:43], v[12:15], v[108:111]
	v_mfma_f32_16x16x32_bf16 v[40:43], v[112:115], v[8:11], v[40:43]
	s_nop 1
	ds_read_b128 v[108:111], v98 offset:28672
	ds_read_b128 v[112:115], v99 offset:32768
	s_waitcnt lgkmcnt(0)
	v_mfma_f32_16x16x32_bf16 v[40:43], v[108:111], v[4:7], v[40:43]
	v_fma_f32 v110, v80, s42, v82
	v_fma_f32 v111, v80, s43, v82
	v_pk_fma_f32 v[108:109], v[80:81], s[50:51], v[82:83] op_sel_hi:[0,1,0]
	v_mfma_f32_16x16x32_bf16 v[40:43], v[116:119], v[0:3], v[40:43]
	s_nop 0
	v_mfma_f32_16x16x32_bf16 v[48:51], v[48:51], v[12:15], v[108:111]
	v_mfma_f32_16x16x32_bf16 v[48:51], v[120:123], v[8:11], v[48:51]
	v_mfma_f32_16x16x32_bf16 v[48:51], v[104:107], v[4:7], v[48:51]
	v_mfma_f32_16x16x32_bf16 v[48:51], v[112:115], v[0:3], v[48:51]
	s_nop 0
	s_waitcnt lgkmcnt(0)
	s_barrier
	v_cndmask_b32_e64 v79, 0, 1, s[66:67]
	v_cmp_ne_u32_e64 s[34:35], 1, v79
	s_andn2_b64 vcc, exec, s[66:67]
	s_cbranch_vccnz .LBB0_455
	s_lshl_b32 s96, s83, 11
	s_cmp_gt_i32 s81, 0
	s_mov_b64 s[66:67], -1
	s_cbranch_scc1 .LBB0_451
	s_add_i32 s95, s96, s79
	s_lshl_b32 s60, s94, 7
	s_mov_b64 s[66:67], 0

; #define LAS __attribute__((address_space(3)))
; #define WG_BAR() do { asm volatile("s_waitcnt lgkmcnt(0)" ::: "memory"); __builtin_amdgcn_s_barrier(); asm volatile("" ::: "memory"); } while (0)
; template <int MODE, class Dec>
; __device__ __forceinline__ void attn_phase(const Frame& F, const bf16* Q, const bf16* K, const bf16* V, int nunits, const Dec dec, const bf16* O3, const float* L2, const float* L3) {
;     ...
;         const int un = u + F.G; const bool has_next = un < nunits; if (has_next) dec(un, nxt);
;         const int n = cur.n, h = cur.h, d = cur.d;
;         const int qi = 16 * w + ql;
;         const size_t qrow = (size_t)(cur.b * SEQ + (n * 128 + qi) * d + cur.r);
;         WG_BAR();
;         const float sl = exp2f(-0.5f * (float)(h + 1)) * LOG2E * (float)d, cb = -sl * (float)(128 + ql - 4 * g);
;         f32x4 s[9];
;         __builtin_amdgcn_s_setprio(1);
; #pragma unroll
;         for (int tt = 0; tt < 9; ++tt) {
;             s[tt] = (f32x4){fmaf(sl, (float)(16 * tt), cb), fmaf(sl, (float)(16 * tt + 1), cb), fmaf(sl, (float)(16 * tt + 2), cb), fmaf(sl, (float)(16 * tt + 3), cb)};
; #pragma unroll
;             for (int ks = 0; ks < 4; ++ks) { const bf16x8 a = *(const LAS bf16x8*)(kb + ksw[ks] + tt * 4096); s[tt] = __builtin_amdgcn_mfma_f32_16x16x32_bf16(a, qf[ks], s[tt], 0, 0, 0); }
;         }
;         __builtin_amdgcn_s_setprio(0);
;         WG_BAR();
.LBB0_539:
	s_cmpk_lt_i32 s62, 0x800
	s_cselect_b64 s[50:51], -1, 0
	s_cmpk_gt_i32 s62, 0x7ff
	s_mov_b32 s92, s34
	s_cselect_b64 s[2:3], -1, 0
	s_lshl_b32 s48, s48, 11
	s_lshl_b32 s66, s65, 7
	s_add_i32 s48, s48, s66
	s_add_i32 s66, s92, 1
	v_cvt_f32_u32_e32 v16, s66
	v_add_u32_e32 v52, s48, v130
	s_mov_b32 s48, 0xc2fc0000
	s_bfe_u32 s34, s62, 0x40004
	v_mul_f32_e32 v17, -0.5, v16
	v_cmp_gt_f32_e32 vcc, s48, v17
	s_ashr_i32 s64, s62, 8
	s_and_b64 s[66:67], vcc, exec
	v_cndmask_b32_e32 v17, 0, v144, vcc
	v_fmac_f32_e32 v17, -0.5, v16
	v_exp_f32_e32 v16, v17
	s_waitcnt lgkmcnt(0)
	s_barrier
	s_cselect_b32 s48, 0xffffffc0, 0
	v_ldexp_f32 v16, v16, s48
	v_mul_f32_e32 v54, 0x3fb8aa3b, v16
	v_mul_f32_e64 v56, v131, -v54
	s_nop 0
	ds_read_b128 v[20:23], v140
	ds_read_b128 v[48:51], v140 offset:28672
	s_mov_b32 s66, 2.0
	s_mov_b32 s67, 0x40400000
	v_fma_f32 v16, 0, v54, v56
	v_fma_f32 v17, v131, -v54, v54
	v_pk_fma_f32 v[18:19], v[54:55], s[66:67], v[56:57] op_sel_hi:[0,1,0]
	s_mov_b32 s66, 0x41900000
	s_mov_b32 s67, 0x41980000
	s_waitcnt lgkmcnt(1)
	v_mfma_f32_16x16x32_bf16 v[16:19], v[20:23], v[0:3], v[16:19]
	ds_read_b128 v[20:23], v141
	v_ashrrev_i32_e32 v53, 31, v52
	s_waitcnt lgkmcnt(0)
	v_mfma_f32_16x16x32_bf16 v[16:19], v[20:23], v[4:7], v[16:19]
	ds_read_b128 v[20:23], v142
	s_waitcnt lgkmcnt(0)
	v_mfma_f32_16x16x32_bf16 v[16:19], v[20:23], v[8:11], v[16:19]
	ds_read_b128 v[20:23], v143
	s_waitcnt lgkmcnt(0)
	v_mfma_f32_16x16x32_bf16 v[44:47], v[20:23], v[12:15], v[16:19]
	ds_read_b128 v[20:23], v140 offset:4096
	s_nop 3
	v_pk_fma_f32 v[18:19], v[54:55], s[66:67], v[56:57] op_sel_hi:[0,1,0]
	s_mov_b32 s66, 0x41800000
	s_mov_b32 s67, 0x41880000
	v_pk_fma_f32 v[16:17], v[54:55], s[66:67], v[56:57] op_sel_hi:[0,1,0]
	s_mov_b32 s66, 0x42080000
	s_mov_b32 s67, 0x420c0000
	s_waitcnt lgkmcnt(0)
	v_mfma_f32_16x16x32_bf16 v[16:19], v[20:23], v[0:3], v[16:19]
	ds_read_b128 v[20:23], v141 offset:4096
	s_waitcnt lgkmcnt(0)
	v_mfma_f32_16x16x32_bf16 v[16:19], v[20:23], v[4:7], v[16:19]
	ds_read_b128 v[20:23], v142 offset:4096
	s_waitcnt lgkmcnt(0)
	v_mfma_f32_16x16x32_bf16 v[16:19], v[20:23], v[8:11], v[16:19]
	ds_read_b128 v[20:23], v143 offset:4096
	s_waitcnt lgkmcnt(0)
	v_mfma_f32_16x16x32_bf16 v[40:43], v[20:23], v[12:15], v[16:19]
	ds_read_b128 v[20:23], v140 offset:8192
	s_nop 3
	v_pk_fma_f32 v[18:19], v[54:55], s[66:67], v[56:57] op_sel_hi:[0,1,0]
	s_mov_b32 s66, 0x42000000
	s_mov_b32 s67, 0x42040000
	v_pk_fma_f32 v[16:17], v[54:55], s[66:67], v[56:57] op_sel_hi:[0,1,0]
	s_mov_b32 s66, 0x42480000
	s_mov_b32 s67, 0x424c0000
	s_waitcnt lgkmcnt(0)
	v_mfma_f32_16x16x32_bf16 v[16:19], v[20:23], v[0:3], v[16:19]
	ds_read_b128 v[20:23], v141 offset:8192
	s_waitcnt lgkmcnt(0)
	v_mfma_f32_16x16x32_bf16 v[16:19], v[20:23], v[4:7], v[16:19]
	ds_read_b128 v[20:23], v142 offset:8192
	s_waitcnt lgkmcnt(0)
	v_mfma_f32_16x16x32_bf16 v[16:19], v[20:23], v[8:11], v[16:19]
	ds_read_b128 v[20:23], v143 offset:8192
	s_waitcnt lgkmcnt(0)
	v_mfma_f32_16x16x32_bf16 v[36:39], v[20:23], v[12:15], v[16:19]
	ds_read_b128 v[20:23], v140 offset:12288
	s_nop 3
	v_pk_fma_f32 v[18:19], v[54:55], s[66:67], v[56:57] op_sel_hi:[0,1,0]
	s_mov_b32 s66, 0x42400000
	s_mov_b32 s67, 0x42440000
	v_pk_fma_f32 v[16:17], v[54:55], s[66:67], v[56:57] op_sel_hi:[0,1,0]
	s_mov_b32 s66, 0x42800000
	s_mov_b32 s67, 0x42820000
	s_waitcnt lgkmcnt(0)
	v_mfma_f32_16x16x32_bf16 v[16:19], v[20:23], v[0:3], v[16:19]
	ds_read_b128 v[20:23], v141 offset:12288
	s_waitcnt lgkmcnt(0)
	v_mfma_f32_16x16x32_bf16 v[16:19], v[20:23], v[4:7], v[16:19]
	ds_read_b128 v[20:23], v142 offset:12288
	s_waitcnt lgkmcnt(0)
	v_mfma_f32_16x16x32_bf16 v[16:19], v[20:23], v[8:11], v[16:19]
	ds_read_b128 v[20:23], v143 offset:12288
	s_waitcnt lgkmcnt(0)
	v_mfma_f32_16x16x32_bf16 v[32:35], v[20:23], v[12:15], v[16:19]
	ds_read_b128 v[20:23], v140 offset:16384
	s_nop 3
	v_pk_fma_f32 v[18:19], v[54:55], s[70:71], v[56:57] op_sel_hi:[0,1,0]
	v_pk_fma_f32 v[16:17], v[54:55], s[66:67], v[56:57] op_sel_hi:[0,1,0]
	s_and_b32 s66, s62, 15
	s_waitcnt lgkmcnt(0)
	v_mfma_f32_16x16x32_bf16 v[16:19], v[20:23], v[0:3], v[16:19]
	ds_read_b128 v[20:23], v141 offset:16384
	s_waitcnt lgkmcnt(0)
	v_mfma_f32_16x16x32_bf16 v[16:19], v[20:23], v[4:7], v[16:19]
	ds_read_b128 v[20:23], v142 offset:16384
	s_waitcnt lgkmcnt(0)
	v_mfma_f32_16x16x32_bf16 v[16:19], v[20:23], v[8:11], v[16:19]
	ds_read_b128 v[20:23], v143 offset:16384
	s_waitcnt lgkmcnt(0)
	v_mfma_f32_16x16x32_bf16 v[28:31], v[20:23], v[12:15], v[16:19]
	ds_read_b128 v[20:23], v140 offset:20480
	s_nop 3
	v_pk_fma_f32 v[18:19], v[54:55], s[72:73], v[56:57] op_sel_hi:[0,1,0]
	v_pk_fma_f32 v[16:17], v[54:55], s[74:75], v[56:57] op_sel_hi:[0,1,0]
	s_waitcnt lgkmcnt(0)
	s_nop 0
	v_mfma_f32_16x16x32_bf16 v[16:19], v[20:23], v[0:3], v[16:19]
	ds_read_b128 v[20:23], v141 offset:20480
	s_waitcnt lgkmcnt(0)
; #define LAS __attribute__((address_space(3)))
; #define WG_BAR() do { asm volatile("s_waitcnt lgkmcnt(0)" ::: "memory"); __builtin_amdgcn_s_barrier(); asm volatile("" ::: "memory"); } while (0)
; template <bool VSW>
; __device__ __forceinline__ void attn_issue(const Frame& F, const bf16* X, const AUnit& a, int ldsoff) {
;     ...
;     for (int i = 0; i < 8; ++i) { const int rg = w + 8 * i, j = 4 * rg + g, jr = j & 15, c = ql ^ (VSW ? (((jr & 7) << 1) | (jr >> 3)) : jr);
;         if (i >= 4 || a.n > 0) {
;             const size_t go = ((size_t)(a.b * SEQ + ((a.n - 1) * 128 + j) * a.d + a.r) * 2048 + a.h * 128 + c * 8) * 2;
;             __builtin_amdgcn_global_load_lds((const unsigned*)((const char*)X + go), (LAS unsigned*)(F.lds + ldsoff + rg * 1024), 16, 0, 0); } }
; template <int MODE, class Dec>
; __device__ __forceinline__ void attn_phase(const Frame& F, const bf16* Q, const bf16* K, const bf16* V, int nunits, const Dec dec, const bf16* O3, const float* L2, const float* L3) {
;     ...
;             for (int ks = 0; ks < 4; ++ks) { const bf16x8 a = *(const LAS bf16x8*)(kb + ksw[ks] + tt * 4096); s[tt] = __builtin_amdgcn_mfma_f32_16x16x32_bf16(a, qf[ks], s[tt], 0, 0, 0); }
;         }
;         __builtin_amdgcn_s_setprio(0);
;         WG_BAR();
;         v2u a2[8], a3[8]; float l2v = 0.f, l3v = 0.f;
;         bf16* op = cur.Og + qrow * (size_t)cur.ldo + h * 128 + 4 * g;
;         if (MODE == 1) { const bf16* o3p = O3 + qrow * 2048 + h * 128 + 4 * g;
; #pragma unroll
;             for (int dt = 0; dt < 8; ++dt) { a2[dt] = *(const v2u*)(op + 16 * dt); a3[dt] = *(const v2u*)(o3p + 16 * dt); }
;             l2v = L2[qrow * 16 + h]; l3v = L3[qrow * 16 + h]; }
;         if (has_next) { attn_issue<false>(F, K, nxt, 0);
;             q_load4(Q + (size_t)(nxt.b * SEQ + (nxt.n * 128 + qi) * nxt.d + nxt.r) * 2048 + nxt.h * 128 + 8 * g, qn); }
	v_mfma_f32_16x16x32_bf16 v[16:19], v[20:23], v[4:7], v[16:19]
	ds_read_b128 v[20:23], v142 offset:20480
	s_waitcnt lgkmcnt(0)
	v_mfma_f32_16x16x32_bf16 v[16:19], v[20:23], v[8:11], v[16:19]
	ds_read_b128 v[20:23], v143 offset:20480
	s_waitcnt lgkmcnt(0)
	v_mfma_f32_16x16x32_bf16 v[24:27], v[20:23], v[12:15], v[16:19]
	ds_read_b128 v[20:23], v140 offset:24576
	s_nop 3
	v_pk_fma_f32 v[18:19], v[54:55], s[76:77], v[56:57] op_sel_hi:[0,1,0]
	v_pk_fma_f32 v[16:17], v[54:55], s[80:81], v[56:57] op_sel_hi:[0,1,0]
	s_waitcnt lgkmcnt(0)
	s_nop 0
	v_mfma_f32_16x16x32_bf16 v[16:19], v[20:23], v[0:3], v[16:19]
	ds_read_b128 v[20:23], v141 offset:24576
	s_waitcnt lgkmcnt(0)
	v_mfma_f32_16x16x32_bf16 v[16:19], v[20:23], v[4:7], v[16:19]
	ds_read_b128 v[20:23], v142 offset:24576
	s_waitcnt lgkmcnt(0)
	v_mfma_f32_16x16x32_bf16 v[16:19], v[20:23], v[8:11], v[16:19]
	ds_read_b128 v[20:23], v143 offset:24576
	s_waitcnt lgkmcnt(0)
	v_mfma_f32_16x16x32_bf16 v[20:23], v[20:23], v[12:15], v[16:19]
	s_nop 4
	v_fma_f32 v18, v54, s96, v56
	v_fma_f32 v19, v54, s97, v56
	v_pk_fma_f32 v[16:17], v[54:55], s[94:95], v[56:57] op_sel_hi:[0,1,0]
	s_nop 1
	v_mfma_f32_16x16x32_bf16 v[16:19], v[48:51], v[0:3], v[16:19]
	ds_read_b128 v[48:51], v141 offset:28672
	s_waitcnt lgkmcnt(0)
	v_mfma_f32_16x16x32_bf16 v[16:19], v[48:51], v[4:7], v[16:19]
	ds_read_b128 v[48:51], v142 offset:28672
	s_waitcnt lgkmcnt(0)
	v_mfma_f32_16x16x32_bf16 v[16:19], v[48:51], v[8:11], v[16:19]
	ds_read_b128 v[48:51], v143 offset:28672
	s_waitcnt lgkmcnt(0)
	v_mfma_f32_16x16x32_bf16 v[16:19], v[48:51], v[12:15], v[16:19]
	v_fma_f32 v50, v54, s78, v56
	v_fma_f32 v51, v54, s79, v56
	v_pk_fma_f32 v[48:49], v[54:55], s[82:83], v[56:57] op_sel_hi:[0,1,0]
	ds_read_b128 v[54:57], v140 offset:32768
	s_waitcnt lgkmcnt(0)
	v_mfma_f32_16x16x32_bf16 v[48:51], v[54:57], v[0:3], v[48:51]
	ds_read_b128 v[54:57], v141 offset:32768
	s_waitcnt lgkmcnt(0)
	v_mfma_f32_16x16x32_bf16 v[48:51], v[54:57], v[4:7], v[48:51]
	ds_read_b128 v[54:57], v142 offset:32768
	s_waitcnt lgkmcnt(0)
	v_mfma_f32_16x16x32_bf16 v[48:51], v[54:57], v[8:11], v[48:51]
	ds_read_b128 v[54:57], v143 offset:32768
	s_waitcnt lgkmcnt(0)
	v_mfma_f32_16x16x32_bf16 v[48:51], v[54:57], v[12:15], v[48:51]
	s_nop 0
	v_lshlrev_b64 v[54:55], 13, v[52:53]
	v_lshl_add_u64 v[54:55], s[86:87], 0, v[54:55]
	s_lshl_b32 s48, s92, 8
	v_lshl_add_u64 v[54:55], v[54:55], 0, s[48:49]
	v_lshl_add_u64 v[92:93], v[54:55], 0, v[74:75]
	v_lshlrev_b64 v[54:55], 12, v[52:53]
	v_lshl_add_u64 v[54:55], s[42:43], 0, v[54:55]
	s_waitcnt lgkmcnt(0)
	s_barrier
	v_lshl_add_u64 v[54:55], v[54:55], 0, s[48:49]
	v_lshl_add_u64 v[54:55], v[54:55], 0, v[74:75]
	v_bfe_u32 v242, v156, 4, 1
	v_mul_u32_u24_e32 v242, 24, v242
	v_mov_b32_e32 v243, 0
	v_lshl_add_u64 v[240:241], v[92:93], 0, v[242:243]
	v_lshl_add_u64 v[244:245], v[54:55], 0, v[242:243]
	global_load_dwordx4 v[94:97], v[240:241], off
	global_load_dwordx4 v[98:101], v[244:245], off
	global_load_dwordx4 v[102:105], v[240:241], off offset:64
	global_load_dwordx4 v[106:109], v[244:245], off offset:64
	global_load_dwordx4 v[110:113], v[240:241], off offset:128
	global_load_dwordx4 v[114:117], v[244:245], off offset:128
	global_load_dwordx4 v[118:121], v[240:241], off offset:192
	global_load_dwordx4 v[122:125], v[244:245], off offset:192
	s_mov_b32 s93, s49
	v_lshlrev_b64 v[52:53], 6, v[52:53]
	s_lshl_b64 s[68:69], s[92:93], 2
	v_or_b32_e32 v53, s69, v53
	v_or_b32_e32 v52, s68, v52
	v_lshl_add_u64 v[54:55], s[44:45], 0, v[52:53]
	v_lshl_add_u64 v[52:53], s[46:47], 0, v[52:53]
	global_load_dword v147, v[54:55], off
	global_load_dword v148, v[52:53], off
	s_and_b64 vcc, exec, s[2:3]
	s_cbranch_vccnz .LBB0_544
	s_lshl_b32 s67, s64, 11
	s_cmp_lg_u32 s66, 0
	s_cbranch_scc0 .LBB0_555
	s_lshl_b32 s68, s66, 7
	s_add_i32 s48, s68, s67
	s_add_i32 s69, s48, 0xffffff80
	v_add_u32_e32 v0, s69, v127
	v_ashrrev_i32_e32 v1, 31, v0
	v_lshlrev_b64 v[0:1], 11, v[0:1]
	s_lshl_b32 s48, s34, 7
	v_or_b32_e32 v0, v0, v82
	v_or_b32_e32 v0, s48, v0
	v_lshl_add_u64 v[0:1], v[0:1], 1, s[36:37]
	s_add_i32 m0, s35, 0
	s_nop 0
	global_load_lds_dwordx4 v[0:1], off
	v_add_u32_e32 v0, s69, v126
	v_ashrrev_i32_e32 v1, 31, v0
	v_lshlrev_b64 v[0:1], 11, v[0:1]
	v_or_b32_e32 v0, v0, v84
	v_or_b32_e32 v0, s48, v0
	v_lshl_add_u64 v[0:1], v[0:1], 1, s[36:37]
	s_add_i32 m0, s54, 0
	s_nop 0
	global_load_lds_dwordx4 v[0:1], off
	v_add_u32_e32 v0, s69, v128
	v_ashrrev_i32_e32 v1, 31, v0
	v_lshlrev_b64 v[0:1], 11, v[0:1]
	v_or_b32_e32 v0, v0, v86
	v_or_b32_e32 v0, s48, v0
	v_lshl_add_u64 v[0:1], v[0:1], 1, s[36:37]
	s_add_i32 m0, s55, 0
	s_nop 0
	global_load_lds_dwordx4 v[0:1], off
	v_add_u32_e32 v0, s69, v129
	v_ashrrev_i32_e32 v1, 31, v0
	v_lshlrev_b64 v[0:1], 11, v[0:1]
	v_or_b32_e32 v0, v0, v88
	v_or_b32_e32 v0, s48, v0
	v_lshl_add_u64 v[0:1], v[0:1], 1, s[36:37]
	s_add_i32 m0, s56, 0
	s_nop 0
	global_load_lds_dwordx4 v[0:1], off
	s_cbranch_execnz .LBB0_543
